# P10 epilogue: conv-tap DPP FMAs issued tap-major (four accumulation chains round-robin)
# baseline (speedup 1.0000x reference)
.LBB0_1518:
	v_readlane_b32 s14, v255, 25
	v_readlane_b32 s15, v255, 26
	v_readlane_b32 s12, v255, 27
	v_readlane_b32 s13, v255, 28
	v_mbcnt_lo_u32_b32 v156, -1, 0
	v_mbcnt_hi_u32_b32 v156, -1, v156
	s_lshl_b32 s8, s4, 7
	s_or_b32 s8, s8, s70
	s_lshl_b32 s9, s6, 8
	s_add_i32 s9, s9, s69
	v_and_b32_e32 v157, 15, v156
	v_lshrrev_b32_e32 v158, 4, v156
	v_lshl_add_u32 v158, v158, 3, s8
	v_add_u32_e32 v159, s9, v157
	v_lshlrev_b32_e32 v160, 2, v159
	v_lshlrev_b32_e32 v161, 2, v158
	s_add_u32 s16, s14, 0x2c00
	s_addc_u32 s17, s15, 0
	s_add_u32 s18, s14, 0x5800
	s_addc_u32 s19, s15, 0
	global_load_dword v148, v160, s[44:45]
	global_load_dword v150, v160, s[44:45] offset:64
	global_load_dword v152, v160, s[44:45] offset:128
	global_load_dword v154, v160, s[44:45] offset:192
	global_load_dword v162, v160, s[44:45] offset:512
	global_load_dword v164, v160, s[44:45] offset:576
	global_load_dword v174, v160, s[44:45] offset:640
	global_load_dword v176, v160, s[44:45] offset:704
	global_load_dwordx4 v[182:185], v161, s[14:15]
	global_load_dwordx4 v[186:189], v161, s[14:15] offset:16
	global_load_dwordx4 v[190:193], v161, s[16:17]
	global_load_dwordx4 v[194:197], v161, s[16:17] offset:16
	global_load_dwordx4 v[198:201], v161, s[18:19]
	global_load_dwordx4 v[202:205], v161, s[18:19] offset:16
	global_load_dwordx4 v[206:209], v161, s[12:13]
	global_load_dwordx4 v[210:213], v161, s[12:13] offset:16
	v_mov_b32_e32 v142, 0xc0135761
	v_mov_b32_e32 v143, 0xc0135761
	v_mov_b32_e32 v144, 0xbdd2d3e8
	v_mov_b32_e32 v145, 0xbdd2d3e8
	v_mov_b32_e32 v146, 1.0
	v_mov_b32_e32 v147, 1.0
	v_mov_b32_e32 v163, 0x358637bd
	v_mul_u32_u24_e32 v225, 0x1600, v159
	v_lshl_add_u32 v225, v158, 1, v225
	v_add_u32_e32 v222, 2, v157
	v_and_b32_e32 v222, 15, v222
	s_lshl_b32 s22, s6, 2
	s_lshr_b32 s23, s69, 6
	s_add_i32 s22, s22, s23
	s_lshl_b32 s22, s22, 2
	s_waitcnt vmcnt(0)
	v_fmamk_f32 v148, v148, 0x3a800000, v163
	v_fmamk_f32 v150, v150, 0x3a800000, v163
	v_fmamk_f32 v152, v152, 0x3a800000, v163
	v_fmamk_f32 v154, v154, 0x3a800000, v163
	v_fmamk_f32 v162, v162, 0x3a800000, v163
	v_fmamk_f32 v164, v164, 0x3a800000, v163
	v_fmamk_f32 v174, v174, 0x3a800000, v163
	v_fmamk_f32 v176, v176, 0x3a800000, v163
	v_rsq_f32_e32 v148, v148
	v_rsq_f32_e32 v150, v150
	v_rsq_f32_e32 v152, v152
	v_rsq_f32_e32 v154, v154
	v_rsq_f32_e32 v162, v162
	v_rsq_f32_e32 v164, v164
	v_rsq_f32_e32 v174, v174
	v_rsq_f32_e32 v176, v176
	s_nop 0
	v_pk_mul_f32 v[124:125], v[124:125], v[148:149] op_sel_hi:[1,0]
	v_pk_mul_f32 v[126:127], v[126:127], v[148:149] op_sel_hi:[1,0]
	v_pk_mul_f32 v[100:101], v[100:101], v[148:149] op_sel_hi:[1,0]
	v_pk_mul_f32 v[102:103], v[102:103], v[148:149] op_sel_hi:[1,0]
	v_pk_mul_f32 v[120:121], v[120:121], v[148:149] op_sel_hi:[1,0]
	v_pk_mul_f32 v[122:123], v[122:123], v[148:149] op_sel_hi:[1,0]
	v_pk_mul_f32 v[88:89], v[88:89], v[148:149] op_sel_hi:[1,0]
	v_pk_mul_f32 v[90:91], v[90:91], v[148:149] op_sel_hi:[1,0]
	v_pk_mul_f32 v[108:109], v[108:109], v[150:151] op_sel_hi:[1,0]
	v_pk_mul_f32 v[110:111], v[110:111], v[150:151] op_sel_hi:[1,0]
	v_pk_mul_f32 v[84:85], v[84:85], v[150:151] op_sel_hi:[1,0]
	v_pk_mul_f32 v[86:87], v[86:87], v[150:151] op_sel_hi:[1,0]
	v_pk_mul_f32 v[96:97], v[96:97], v[150:151] op_sel_hi:[1,0]
	v_pk_mul_f32 v[98:99], v[98:99], v[150:151] op_sel_hi:[1,0]
	v_pk_mul_f32 v[76:77], v[76:77], v[150:151] op_sel_hi:[1,0]
	v_pk_mul_f32 v[78:79], v[78:79], v[150:151] op_sel_hi:[1,0]
	v_pk_mul_f32 v[104:105], v[104:105], v[152:153] op_sel_hi:[1,0]
	v_pk_mul_f32 v[106:107], v[106:107], v[152:153] op_sel_hi:[1,0]
	v_pk_mul_f32 v[80:81], v[80:81], v[152:153] op_sel_hi:[1,0]
	v_pk_mul_f32 v[82:83], v[82:83], v[152:153] op_sel_hi:[1,0]
	v_pk_mul_f32 v[92:93], v[92:93], v[152:153] op_sel_hi:[1,0]
	v_pk_mul_f32 v[94:95], v[94:95], v[152:153] op_sel_hi:[1,0]
	v_pk_mul_f32 v[68:69], v[68:69], v[152:153] op_sel_hi:[1,0]
	v_pk_mul_f32 v[70:71], v[70:71], v[152:153] op_sel_hi:[1,0]
	v_pk_mul_f32 v[116:117], v[116:117], v[154:155] op_sel_hi:[1,0]
	v_pk_mul_f32 v[118:119], v[118:119], v[154:155] op_sel_hi:[1,0]
	v_pk_mul_f32 v[72:73], v[72:73], v[154:155] op_sel_hi:[1,0]
	v_pk_mul_f32 v[74:75], v[74:75], v[154:155] op_sel_hi:[1,0]
	v_pk_mul_f32 v[112:113], v[112:113], v[154:155] op_sel_hi:[1,0]
	v_pk_mul_f32 v[114:115], v[114:115], v[154:155] op_sel_hi:[1,0]
	v_pk_mul_f32 v[64:65], v[64:65], v[154:155] op_sel_hi:[1,0]
	v_pk_mul_f32 v[66:67], v[66:67], v[154:155] op_sel_hi:[1,0]
	v_cmp_gt_u32_e32 vcc, 2, v157
	v_cvt_pk_bf16_f32 v214, v124, v125
	v_cvt_pk_bf16_f32 v215, v126, v127
	v_cvt_pk_bf16_f32 v216, v120, v121
	v_cvt_pk_bf16_f32 v217, v122, v123
	v_cvt_pk_bf16_f32 v218, v116, v117
	v_cvt_pk_bf16_f32 v219, v118, v119
	v_cvt_pk_bf16_f32 v220, v112, v113
	v_cvt_pk_bf16_f32 v221, v114, v115
	v_cndmask_b32_e32 v214, v218, v214, vcc
	v_cndmask_b32_e32 v215, v219, v215, vcc
	v_cndmask_b32_e32 v216, v220, v216, vcc
	v_cndmask_b32_e32 v217, v221, v217, vcc
	v_and_b32_e32 v223, 3, v222
	v_add_u32_e32 v223, s22, v223
	v_mul_u32_u24_e32 v223, 0x1600, v223
	v_lshl_add_u32 v224, v158, 1, v223
	v_cmp_gt_u32_e64 s[10:11], 4, v222
	s_and_saveexec_b64 s[20:21], s[10:11]
	global_store_dwordx4 v224, v[214:217], s[48:49]
	s_mov_b64 exec, s[20:21]
	s_nop 4
	v_pk_fma_f32 v[226:227], v[116:117], v[198:199], v[206:207]
	v_pk_fma_f32 v[230:231], v[112:113], v[202:203], v[210:211]
	v_pk_fma_f32 v[228:229], v[118:119], v[200:201], v[208:209]
	v_pk_fma_f32 v[232:233], v[114:115], v[204:205], v[212:213]
	v_fmac_f32_dpp v226, v116, v190 row_shr:1 row_mask:0xf bank_mask:0xf
	v_fmac_f32_dpp v230, v112, v194 row_shr:1 row_mask:0xf bank_mask:0xf
	v_fmac_f32_dpp v227, v117, v191 row_shr:1 row_mask:0xf bank_mask:0xf
	v_fmac_f32_dpp v231, v113, v195 row_shr:1 row_mask:0xf bank_mask:0xf
	v_fmac_f32_dpp v228, v118, v192 row_shr:1 row_mask:0xf bank_mask:0xf
	v_fmac_f32_dpp v232, v114, v196 row_shr:1 row_mask:0xf bank_mask:0xf
	v_fmac_f32_dpp v229, v119, v193 row_shr:1 row_mask:0xf bank_mask:0xf
	v_fmac_f32_dpp v233, v115, v197 row_shr:1 row_mask:0xf bank_mask:0xf
	v_fmac_f32_dpp v226, v104, v190 row_shl:15 row_mask:0xf bank_mask:0xf
	v_fmac_f32_dpp v230, v92, v194 row_shl:15 row_mask:0xf bank_mask:0xf
	v_fmac_f32_dpp v227, v105, v191 row_shl:15 row_mask:0xf bank_mask:0xf
	v_fmac_f32_dpp v231, v93, v195 row_shl:15 row_mask:0xf bank_mask:0xf
	v_fmac_f32_dpp v228, v106, v192 row_shl:15 row_mask:0xf bank_mask:0xf
	v_fmac_f32_dpp v232, v94, v196 row_shl:15 row_mask:0xf bank_mask:0xf
	v_fmac_f32_dpp v229, v107, v193 row_shl:15 row_mask:0xf bank_mask:0xf
	v_fmac_f32_dpp v233, v95, v197 row_shl:15 row_mask:0xf bank_mask:0xf
	v_fmac_f32_dpp v226, v116, v182 row_shr:2 row_mask:0xf bank_mask:0xf
	v_fmac_f32_dpp v230, v112, v186 row_shr:2 row_mask:0xf bank_mask:0xf
	v_fmac_f32_dpp v227, v117, v183 row_shr:2 row_mask:0xf bank_mask:0xf
	v_fmac_f32_dpp v231, v113, v187 row_shr:2 row_mask:0xf bank_mask:0xf
	v_fmac_f32_dpp v228, v118, v184 row_shr:2 row_mask:0xf bank_mask:0xf
	v_fmac_f32_dpp v232, v114, v188 row_shr:2 row_mask:0xf bank_mask:0xf
	v_fmac_f32_dpp v229, v119, v185 row_shr:2 row_mask:0xf bank_mask:0xf
	v_fmac_f32_dpp v233, v115, v189 row_shr:2 row_mask:0xf bank_mask:0xf
	v_fmac_f32_dpp v226, v104, v182 row_shl:14 row_mask:0xf bank_mask:0xf
	v_fmac_f32_dpp v230, v92, v186 row_shl:14 row_mask:0xf bank_mask:0xf
	v_fmac_f32_dpp v227, v105, v183 row_shl:14 row_mask:0xf bank_mask:0xf
	v_fmac_f32_dpp v231, v93, v187 row_shl:14 row_mask:0xf bank_mask:0xf
	v_fmac_f32_dpp v228, v106, v184 row_shl:14 row_mask:0xf bank_mask:0xf
	v_fmac_f32_dpp v232, v94, v188 row_shl:14 row_mask:0xf bank_mask:0xf
	v_fmac_f32_dpp v229, v107, v185 row_shl:14 row_mask:0xf bank_mask:0xf
	v_fmac_f32_dpp v233, v95, v189 row_shl:14 row_mask:0xf bank_mask:0xf
	v_pk_mul_f32 v[234:235], v[226:227], v[226:227]
	v_pk_mul_f32 v[238:239], v[230:231], v[230:231]
	v_pk_mul_f32 v[236:237], v[228:229], v[228:229]
	v_pk_mul_f32 v[240:241], v[232:233], v[232:233]
	v_pk_fma_f32 v[234:235], v[234:235], v[144:145], v[142:143]
	v_pk_fma_f32 v[238:239], v[238:239], v[144:145], v[142:143]
	v_pk_fma_f32 v[236:237], v[236:237], v[144:145], v[142:143]
	v_pk_fma_f32 v[240:241], v[240:241], v[144:145], v[142:143]
	v_pk_mul_f32 v[234:235], v[234:235], v[226:227]
	v_pk_mul_f32 v[238:239], v[238:239], v[230:231]
	v_pk_mul_f32 v[236:237], v[236:237], v[228:229]
	v_pk_mul_f32 v[240:241], v[240:241], v[232:233]
	v_exp_f32_e32 v234, v234
	v_exp_f32_e32 v238, v238
	v_exp_f32_e32 v235, v235
	v_exp_f32_e32 v239, v239
	v_exp_f32_e32 v236, v236
	v_exp_f32_e32 v240, v240
	v_exp_f32_e32 v237, v237
	v_exp_f32_e32 v241, v241
	s_nop 0
	s_nop 0
	v_pk_add_f32 v[234:235], v[234:235], v[146:147]
	v_pk_add_f32 v[238:239], v[238:239], v[146:147]
	v_pk_add_f32 v[236:237], v[236:237], v[146:147]
	v_pk_add_f32 v[240:241], v[240:241], v[146:147]
	v_rcp_f32_e32 v234, v234
	v_rcp_f32_e32 v238, v238
	v_rcp_f32_e32 v235, v235
	v_rcp_f32_e32 v239, v239
	v_rcp_f32_e32 v236, v236
	v_rcp_f32_e32 v240, v240
	v_rcp_f32_e32 v237, v237
	v_rcp_f32_e32 v241, v241
	s_nop 0
	s_nop 0
	v_pk_mul_f32 v[234:235], v[234:235], v[226:227]
	v_pk_mul_f32 v[238:239], v[238:239], v[230:231]
	v_pk_mul_f32 v[236:237], v[236:237], v[228:229]
	v_pk_mul_f32 v[240:241], v[240:241], v[232:233]
	v_pk_mul_f32 v[72:73], v[72:73], v[234:235]
	v_pk_mul_f32 v[64:65], v[64:65], v[238:239]
	v_pk_mul_f32 v[74:75], v[74:75], v[236:237]
	v_pk_mul_f32 v[66:67], v[66:67], v[240:241]
	v_cvt_pk_bf16_f32 v72, v72, v73
	v_cvt_pk_bf16_f32 v73, v74, v75
	v_cvt_pk_bf16_f32 v74, v64, v65
	v_cvt_pk_bf16_f32 v75, v66, v67
	v_add_u32_e32 v245, 0x42000, v225
	global_store_dwordx4 v245, v[72:75], s[46:47]
	v_pk_fma_f32 v[226:227], v[104:105], v[198:199], v[206:207]
	v_pk_fma_f32 v[230:231], v[92:93], v[202:203], v[210:211]
	v_pk_fma_f32 v[228:229], v[106:107], v[200:201], v[208:209]
	v_pk_fma_f32 v[232:233], v[94:95], v[204:205], v[212:213]
	v_fmac_f32_dpp v226, v104, v190 row_shr:1 row_mask:0xf bank_mask:0xf
	v_fmac_f32_dpp v230, v92, v194 row_shr:1 row_mask:0xf bank_mask:0xf
	v_fmac_f32_dpp v227, v105, v191 row_shr:1 row_mask:0xf bank_mask:0xf
	v_fmac_f32_dpp v231, v93, v195 row_shr:1 row_mask:0xf bank_mask:0xf
	v_fmac_f32_dpp v228, v106, v192 row_shr:1 row_mask:0xf bank_mask:0xf
	v_fmac_f32_dpp v232, v94, v196 row_shr:1 row_mask:0xf bank_mask:0xf
	v_fmac_f32_dpp v229, v107, v193 row_shr:1 row_mask:0xf bank_mask:0xf
	v_fmac_f32_dpp v233, v95, v197 row_shr:1 row_mask:0xf bank_mask:0xf
	v_fmac_f32_dpp v226, v108, v190 row_shl:15 row_mask:0xf bank_mask:0xf
	v_fmac_f32_dpp v230, v96, v194 row_shl:15 row_mask:0xf bank_mask:0xf
	v_fmac_f32_dpp v227, v109, v191 row_shl:15 row_mask:0xf bank_mask:0xf
	v_fmac_f32_dpp v231, v97, v195 row_shl:15 row_mask:0xf bank_mask:0xf
	v_fmac_f32_dpp v228, v110, v192 row_shl:15 row_mask:0xf bank_mask:0xf
	v_fmac_f32_dpp v232, v98, v196 row_shl:15 row_mask:0xf bank_mask:0xf
	v_fmac_f32_dpp v229, v111, v193 row_shl:15 row_mask:0xf bank_mask:0xf
	v_fmac_f32_dpp v233, v99, v197 row_shl:15 row_mask:0xf bank_mask:0xf
	v_fmac_f32_dpp v226, v104, v182 row_shr:2 row_mask:0xf bank_mask:0xf
	v_fmac_f32_dpp v230, v92, v186 row_shr:2 row_mask:0xf bank_mask:0xf
	v_fmac_f32_dpp v227, v105, v183 row_shr:2 row_mask:0xf bank_mask:0xf
	v_fmac_f32_dpp v231, v93, v187 row_shr:2 row_mask:0xf bank_mask:0xf
	v_fmac_f32_dpp v228, v106, v184 row_shr:2 row_mask:0xf bank_mask:0xf
	v_fmac_f32_dpp v232, v94, v188 row_shr:2 row_mask:0xf bank_mask:0xf
	v_fmac_f32_dpp v229, v107, v185 row_shr:2 row_mask:0xf bank_mask:0xf
	v_fmac_f32_dpp v233, v95, v189 row_shr:2 row_mask:0xf bank_mask:0xf
	v_fmac_f32_dpp v226, v108, v182 row_shl:14 row_mask:0xf bank_mask:0xf
	v_fmac_f32_dpp v230, v96, v186 row_shl:14 row_mask:0xf bank_mask:0xf
	v_fmac_f32_dpp v227, v109, v183 row_shl:14 row_mask:0xf bank_mask:0xf
	v_fmac_f32_dpp v231, v97, v187 row_shl:14 row_mask:0xf bank_mask:0xf
	v_fmac_f32_dpp v228, v110, v184 row_shl:14 row_mask:0xf bank_mask:0xf
	v_fmac_f32_dpp v232, v98, v188 row_shl:14 row_mask:0xf bank_mask:0xf
	v_fmac_f32_dpp v229, v111, v185 row_shl:14 row_mask:0xf bank_mask:0xf
	v_fmac_f32_dpp v233, v99, v189 row_shl:14 row_mask:0xf bank_mask:0xf
	v_pk_mul_f32 v[234:235], v[226:227], v[226:227]
	v_pk_mul_f32 v[238:239], v[230:231], v[230:231]
	v_pk_mul_f32 v[236:237], v[228:229], v[228:229]
	v_pk_mul_f32 v[240:241], v[232:233], v[232:233]
	v_pk_fma_f32 v[234:235], v[234:235], v[144:145], v[142:143]
	v_pk_fma_f32 v[238:239], v[238:239], v[144:145], v[142:143]
	v_pk_fma_f32 v[236:237], v[236:237], v[144:145], v[142:143]
	v_pk_fma_f32 v[240:241], v[240:241], v[144:145], v[142:143]
	v_pk_mul_f32 v[234:235], v[234:235], v[226:227]
	v_pk_mul_f32 v[238:239], v[238:239], v[230:231]
	v_pk_mul_f32 v[236:237], v[236:237], v[228:229]
	v_pk_mul_f32 v[240:241], v[240:241], v[232:233]
	v_exp_f32_e32 v234, v234
	v_exp_f32_e32 v238, v238
	v_exp_f32_e32 v235, v235
	v_exp_f32_e32 v239, v239
	v_exp_f32_e32 v236, v236
	v_exp_f32_e32 v240, v240
	v_exp_f32_e32 v237, v237
	v_exp_f32_e32 v241, v241
	s_nop 0
	s_nop 0
	v_pk_add_f32 v[234:235], v[234:235], v[146:147]
	v_pk_add_f32 v[238:239], v[238:239], v[146:147]
	v_pk_add_f32 v[236:237], v[236:237], v[146:147]
	v_pk_add_f32 v[240:241], v[240:241], v[146:147]
	v_rcp_f32_e32 v234, v234
	v_rcp_f32_e32 v238, v238
	v_rcp_f32_e32 v235, v235
	v_rcp_f32_e32 v239, v239
	v_rcp_f32_e32 v236, v236
	v_rcp_f32_e32 v240, v240
	v_rcp_f32_e32 v237, v237
	v_rcp_f32_e32 v241, v241
	s_nop 0
	s_nop 0
	v_pk_mul_f32 v[234:235], v[234:235], v[226:227]
	v_pk_mul_f32 v[238:239], v[238:239], v[230:231]
	v_pk_mul_f32 v[236:237], v[236:237], v[228:229]
	v_pk_mul_f32 v[240:241], v[240:241], v[232:233]
	v_pk_mul_f32 v[80:81], v[80:81], v[234:235]
	v_pk_mul_f32 v[68:69], v[68:69], v[238:239]
	v_pk_mul_f32 v[82:83], v[82:83], v[236:237]
	v_pk_mul_f32 v[70:71], v[70:71], v[240:241]
	v_cvt_pk_bf16_f32 v80, v80, v81
	v_cvt_pk_bf16_f32 v81, v82, v83
	v_cvt_pk_bf16_f32 v82, v68, v69
	v_cvt_pk_bf16_f32 v83, v70, v71
	v_add_u32_e32 v244, 0x2c000, v225
	global_store_dwordx4 v244, v[80:83], s[46:47]
	v_pk_fma_f32 v[226:227], v[108:109], v[198:199], v[206:207]
	v_pk_fma_f32 v[230:231], v[96:97], v[202:203], v[210:211]
	v_pk_fma_f32 v[228:229], v[110:111], v[200:201], v[208:209]
	v_pk_fma_f32 v[232:233], v[98:99], v[204:205], v[212:213]
	v_fmac_f32_dpp v226, v108, v190 row_shr:1 row_mask:0xf bank_mask:0xf
	v_fmac_f32_dpp v230, v96, v194 row_shr:1 row_mask:0xf bank_mask:0xf
	v_fmac_f32_dpp v227, v109, v191 row_shr:1 row_mask:0xf bank_mask:0xf
	v_fmac_f32_dpp v231, v97, v195 row_shr:1 row_mask:0xf bank_mask:0xf
	v_fmac_f32_dpp v228, v110, v192 row_shr:1 row_mask:0xf bank_mask:0xf
	v_fmac_f32_dpp v232, v98, v196 row_shr:1 row_mask:0xf bank_mask:0xf
	v_fmac_f32_dpp v229, v111, v193 row_shr:1 row_mask:0xf bank_mask:0xf
	v_fmac_f32_dpp v233, v99, v197 row_shr:1 row_mask:0xf bank_mask:0xf
	v_fmac_f32_dpp v226, v124, v190 row_shl:15 row_mask:0xf bank_mask:0xf
	v_fmac_f32_dpp v230, v120, v194 row_shl:15 row_mask:0xf bank_mask:0xf
	v_fmac_f32_dpp v227, v125, v191 row_shl:15 row_mask:0xf bank_mask:0xf
	v_fmac_f32_dpp v231, v121, v195 row_shl:15 row_mask:0xf bank_mask:0xf
	v_fmac_f32_dpp v228, v126, v192 row_shl:15 row_mask:0xf bank_mask:0xf
	v_fmac_f32_dpp v232, v122, v196 row_shl:15 row_mask:0xf bank_mask:0xf
	v_fmac_f32_dpp v229, v127, v193 row_shl:15 row_mask:0xf bank_mask:0xf
	v_fmac_f32_dpp v233, v123, v197 row_shl:15 row_mask:0xf bank_mask:0xf
	v_fmac_f32_dpp v226, v108, v182 row_shr:2 row_mask:0xf bank_mask:0xf
	v_fmac_f32_dpp v230, v96, v186 row_shr:2 row_mask:0xf bank_mask:0xf
	v_fmac_f32_dpp v227, v109, v183 row_shr:2 row_mask:0xf bank_mask:0xf
	v_fmac_f32_dpp v231, v97, v187 row_shr:2 row_mask:0xf bank_mask:0xf
	v_fmac_f32_dpp v228, v110, v184 row_shr:2 row_mask:0xf bank_mask:0xf
	v_fmac_f32_dpp v232, v98, v188 row_shr:2 row_mask:0xf bank_mask:0xf
	v_fmac_f32_dpp v229, v111, v185 row_shr:2 row_mask:0xf bank_mask:0xf
	v_fmac_f32_dpp v233, v99, v189 row_shr:2 row_mask:0xf bank_mask:0xf
	v_fmac_f32_dpp v226, v124, v182 row_shl:14 row_mask:0xf bank_mask:0xf
	v_fmac_f32_dpp v230, v120, v186 row_shl:14 row_mask:0xf bank_mask:0xf
	v_fmac_f32_dpp v227, v125, v183 row_shl:14 row_mask:0xf bank_mask:0xf
	v_fmac_f32_dpp v231, v121, v187 row_shl:14 row_mask:0xf bank_mask:0xf
	v_fmac_f32_dpp v228, v126, v184 row_shl:14 row_mask:0xf bank_mask:0xf
	v_fmac_f32_dpp v232, v122, v188 row_shl:14 row_mask:0xf bank_mask:0xf
	v_fmac_f32_dpp v229, v127, v185 row_shl:14 row_mask:0xf bank_mask:0xf
	v_fmac_f32_dpp v233, v123, v189 row_shl:14 row_mask:0xf bank_mask:0xf
	v_pk_mul_f32 v[234:235], v[226:227], v[226:227]
	v_pk_mul_f32 v[238:239], v[230:231], v[230:231]
	v_pk_mul_f32 v[236:237], v[228:229], v[228:229]
	v_pk_mul_f32 v[240:241], v[232:233], v[232:233]
	v_pk_fma_f32 v[234:235], v[234:235], v[144:145], v[142:143]
	v_pk_fma_f32 v[238:239], v[238:239], v[144:145], v[142:143]
	v_pk_fma_f32 v[236:237], v[236:237], v[144:145], v[142:143]
	v_pk_fma_f32 v[240:241], v[240:241], v[144:145], v[142:143]
	v_pk_mul_f32 v[234:235], v[234:235], v[226:227]
	v_pk_mul_f32 v[238:239], v[238:239], v[230:231]
	v_pk_mul_f32 v[236:237], v[236:237], v[228:229]
	v_pk_mul_f32 v[240:241], v[240:241], v[232:233]
	v_exp_f32_e32 v234, v234
	v_exp_f32_e32 v238, v238
	v_exp_f32_e32 v235, v235
	v_exp_f32_e32 v239, v239
	v_exp_f32_e32 v236, v236
	v_exp_f32_e32 v240, v240
	v_exp_f32_e32 v237, v237
	v_exp_f32_e32 v241, v241
	s_nop 0
	s_nop 0
	v_pk_add_f32 v[234:235], v[234:235], v[146:147]
	v_pk_add_f32 v[238:239], v[238:239], v[146:147]
	v_pk_add_f32 v[236:237], v[236:237], v[146:147]
	v_pk_add_f32 v[240:241], v[240:241], v[146:147]
	v_rcp_f32_e32 v234, v234
	v_rcp_f32_e32 v238, v238
	v_rcp_f32_e32 v235, v235
	v_rcp_f32_e32 v239, v239
	v_rcp_f32_e32 v236, v236
	v_rcp_f32_e32 v240, v240
	v_rcp_f32_e32 v237, v237
	v_rcp_f32_e32 v241, v241
	s_nop 0
	s_nop 0
	v_pk_mul_f32 v[234:235], v[234:235], v[226:227]
	v_pk_mul_f32 v[238:239], v[238:239], v[230:231]
	v_pk_mul_f32 v[236:237], v[236:237], v[228:229]
	v_pk_mul_f32 v[240:241], v[240:241], v[232:233]
	v_pk_mul_f32 v[84:85], v[84:85], v[234:235]
	v_pk_mul_f32 v[76:77], v[76:77], v[238:239]
	v_pk_mul_f32 v[86:87], v[86:87], v[236:237]
	v_pk_mul_f32 v[78:79], v[78:79], v[240:241]
	v_cvt_pk_bf16_f32 v84, v84, v85
	v_cvt_pk_bf16_f32 v85, v86, v87
	v_cvt_pk_bf16_f32 v86, v76, v77
	v_cvt_pk_bf16_f32 v87, v78, v79
	v_add_u32_e32 v243, 0x16000, v225
	global_store_dwordx4 v243, v[84:87], s[46:47]
	v_pk_fma_f32 v[226:227], v[124:125], v[198:199], v[206:207]
	v_pk_fma_f32 v[230:231], v[120:121], v[202:203], v[210:211]
	v_pk_fma_f32 v[228:229], v[126:127], v[200:201], v[208:209]
	v_pk_fma_f32 v[232:233], v[122:123], v[204:205], v[212:213]
	v_fmac_f32_dpp v226, v124, v190 row_shr:1 row_mask:0xf bank_mask:0xf
	v_fmac_f32_dpp v230, v120, v194 row_shr:1 row_mask:0xf bank_mask:0xf
	v_fmac_f32_dpp v227, v125, v191 row_shr:1 row_mask:0xf bank_mask:0xf
	v_fmac_f32_dpp v231, v121, v195 row_shr:1 row_mask:0xf bank_mask:0xf
	v_fmac_f32_dpp v228, v126, v192 row_shr:1 row_mask:0xf bank_mask:0xf
	v_fmac_f32_dpp v232, v122, v196 row_shr:1 row_mask:0xf bank_mask:0xf
	v_fmac_f32_dpp v229, v127, v193 row_shr:1 row_mask:0xf bank_mask:0xf
	v_fmac_f32_dpp v233, v123, v197 row_shr:1 row_mask:0xf bank_mask:0xf
	v_fmac_f32_dpp v226, v124, v182 row_shr:2 row_mask:0xf bank_mask:0xf
	v_fmac_f32_dpp v230, v120, v186 row_shr:2 row_mask:0xf bank_mask:0xf
	v_fmac_f32_dpp v227, v125, v183 row_shr:2 row_mask:0xf bank_mask:0xf
	v_fmac_f32_dpp v231, v121, v187 row_shr:2 row_mask:0xf bank_mask:0xf
	v_fmac_f32_dpp v228, v126, v184 row_shr:2 row_mask:0xf bank_mask:0xf
	v_fmac_f32_dpp v232, v122, v188 row_shr:2 row_mask:0xf bank_mask:0xf
	v_fmac_f32_dpp v229, v127, v185 row_shr:2 row_mask:0xf bank_mask:0xf
	v_fmac_f32_dpp v233, v123, v189 row_shr:2 row_mask:0xf bank_mask:0xf
	v_pk_mul_f32 v[234:235], v[226:227], v[226:227]
	v_pk_mul_f32 v[238:239], v[230:231], v[230:231]
	v_pk_mul_f32 v[236:237], v[228:229], v[228:229]
	v_pk_mul_f32 v[240:241], v[232:233], v[232:233]
	v_pk_fma_f32 v[234:235], v[234:235], v[144:145], v[142:143]
	v_pk_fma_f32 v[238:239], v[238:239], v[144:145], v[142:143]
	v_pk_fma_f32 v[236:237], v[236:237], v[144:145], v[142:143]
	v_pk_fma_f32 v[240:241], v[240:241], v[144:145], v[142:143]
	v_pk_mul_f32 v[234:235], v[234:235], v[226:227]
	v_pk_mul_f32 v[238:239], v[238:239], v[230:231]
	v_pk_mul_f32 v[236:237], v[236:237], v[228:229]
	v_pk_mul_f32 v[240:241], v[240:241], v[232:233]
	v_exp_f32_e32 v234, v234
	v_exp_f32_e32 v238, v238
	v_exp_f32_e32 v235, v235
	v_exp_f32_e32 v239, v239
	v_exp_f32_e32 v236, v236
	v_exp_f32_e32 v240, v240
	v_exp_f32_e32 v237, v237
	v_exp_f32_e32 v241, v241
	s_nop 0
	s_nop 0
	v_pk_add_f32 v[234:235], v[234:235], v[146:147]
	v_pk_add_f32 v[238:239], v[238:239], v[146:147]
	v_pk_add_f32 v[236:237], v[236:237], v[146:147]
	v_pk_add_f32 v[240:241], v[240:241], v[146:147]
	v_rcp_f32_e32 v234, v234
	v_rcp_f32_e32 v238, v238
	v_rcp_f32_e32 v235, v235
	v_rcp_f32_e32 v239, v239
	v_rcp_f32_e32 v236, v236
	v_rcp_f32_e32 v240, v240
	v_rcp_f32_e32 v237, v237
	v_rcp_f32_e32 v241, v241
	s_nop 0
	s_nop 0
	v_pk_mul_f32 v[234:235], v[234:235], v[226:227]
	v_pk_mul_f32 v[238:239], v[238:239], v[230:231]
	v_pk_mul_f32 v[236:237], v[236:237], v[228:229]
	v_pk_mul_f32 v[240:241], v[240:241], v[232:233]
	v_pk_mul_f32 v[234:235], v[100:101], v[234:235]
	v_pk_mul_f32 v[238:239], v[88:89], v[238:239]
	v_pk_mul_f32 v[236:237], v[102:103], v[236:237]
	v_pk_mul_f32 v[240:241], v[90:91], v[240:241]
	v_cndmask_b32_e32 v100, v234, v100, vcc
	v_cndmask_b32_e32 v88, v238, v88, vcc
	v_cndmask_b32_e32 v101, v235, v101, vcc
	v_cndmask_b32_e32 v89, v239, v89, vcc
	v_cndmask_b32_e32 v102, v236, v102, vcc
	v_cndmask_b32_e32 v90, v240, v90, vcc
	v_cndmask_b32_e32 v103, v237, v103, vcc
	v_cndmask_b32_e32 v91, v241, v91, vcc
	v_cvt_pk_bf16_f32 v100, v100, v101
	v_cvt_pk_bf16_f32 v101, v102, v103
	v_cvt_pk_bf16_f32 v102, v88, v89
	v_cvt_pk_bf16_f32 v103, v90, v91
	v_mov_b32_e32 v242, v225
	global_store_dwordx4 v242, v[100:103], s[46:47]
	v_pk_mul_f32 v[60:61], v[60:61], v[162:163] op_sel_hi:[1,0]
	v_pk_mul_f32 v[62:63], v[62:63], v[162:163] op_sel_hi:[1,0]
	v_pk_mul_f32 v[36:37], v[36:37], v[162:163] op_sel_hi:[1,0]
	v_pk_mul_f32 v[38:39], v[38:39], v[162:163] op_sel_hi:[1,0]
	v_pk_mul_f32 v[56:57], v[56:57], v[162:163] op_sel_hi:[1,0]
	v_pk_mul_f32 v[58:59], v[58:59], v[162:163] op_sel_hi:[1,0]
	v_pk_mul_f32 v[24:25], v[24:25], v[162:163] op_sel_hi:[1,0]
	v_pk_mul_f32 v[26:27], v[26:27], v[162:163] op_sel_hi:[1,0]
	v_pk_mul_f32 v[44:45], v[44:45], v[164:165] op_sel_hi:[1,0]
	v_pk_mul_f32 v[46:47], v[46:47], v[164:165] op_sel_hi:[1,0]
	v_pk_mul_f32 v[20:21], v[20:21], v[164:165] op_sel_hi:[1,0]
	v_pk_mul_f32 v[22:23], v[22:23], v[164:165] op_sel_hi:[1,0]
	v_pk_mul_f32 v[32:33], v[32:33], v[164:165] op_sel_hi:[1,0]
	v_pk_mul_f32 v[34:35], v[34:35], v[164:165] op_sel_hi:[1,0]
	v_pk_mul_f32 v[12:13], v[12:13], v[164:165] op_sel_hi:[1,0]
	v_pk_mul_f32 v[14:15], v[14:15], v[164:165] op_sel_hi:[1,0]
	v_pk_mul_f32 v[40:41], v[40:41], v[174:175] op_sel_hi:[1,0]
	v_pk_mul_f32 v[42:43], v[42:43], v[174:175] op_sel_hi:[1,0]
	v_pk_mul_f32 v[16:17], v[16:17], v[174:175] op_sel_hi:[1,0]
	v_pk_mul_f32 v[18:19], v[18:19], v[174:175] op_sel_hi:[1,0]
	v_pk_mul_f32 v[28:29], v[28:29], v[174:175] op_sel_hi:[1,0]
	v_pk_mul_f32 v[30:31], v[30:31], v[174:175] op_sel_hi:[1,0]
	v_pk_mul_f32 v[4:5], v[4:5], v[174:175] op_sel_hi:[1,0]
	v_pk_mul_f32 v[6:7], v[6:7], v[174:175] op_sel_hi:[1,0]
	v_pk_mul_f32 v[52:53], v[52:53], v[176:177] op_sel_hi:[1,0]
	v_pk_mul_f32 v[54:55], v[54:55], v[176:177] op_sel_hi:[1,0]
	v_pk_mul_f32 v[8:9], v[8:9], v[176:177] op_sel_hi:[1,0]
	v_pk_mul_f32 v[10:11], v[10:11], v[176:177] op_sel_hi:[1,0]
	v_pk_mul_f32 v[48:49], v[48:49], v[176:177] op_sel_hi:[1,0]
	v_pk_mul_f32 v[50:51], v[50:51], v[176:177] op_sel_hi:[1,0]
	v_pk_mul_f32 v[0:1], v[0:1], v[176:177] op_sel_hi:[1,0]
	v_pk_mul_f32 v[2:3], v[2:3], v[176:177] op_sel_hi:[1,0]
	v_cmp_gt_u32_e32 vcc, 2, v157
	v_cvt_pk_bf16_f32 v214, v60, v61
	v_cvt_pk_bf16_f32 v215, v62, v63
	v_cvt_pk_bf16_f32 v216, v56, v57
	v_cvt_pk_bf16_f32 v217, v58, v59
	v_cvt_pk_bf16_f32 v218, v52, v53
	v_cvt_pk_bf16_f32 v219, v54, v55
	v_cvt_pk_bf16_f32 v220, v48, v49
	v_cvt_pk_bf16_f32 v221, v50, v51
	v_cndmask_b32_e32 v214, v218, v214, vcc
	v_cndmask_b32_e32 v215, v219, v215, vcc
	v_cndmask_b32_e32 v216, v220, v216, vcc
	v_cndmask_b32_e32 v217, v221, v217, vcc
	v_and_b32_e32 v223, 3, v222
	v_add3_u32 v223, s22, v223, 8
	v_mul_u32_u24_e32 v223, 0x1600, v223
	v_lshl_add_u32 v224, v158, 1, v223
	v_cmp_gt_u32_e64 s[10:11], 4, v222
	s_and_saveexec_b64 s[20:21], s[10:11]
	global_store_dwordx4 v224, v[214:217], s[48:49]
	s_mov_b64 exec, s[20:21]
	s_nop 4
	v_pk_fma_f32 v[226:227], v[52:53], v[198:199], v[206:207]
	v_pk_fma_f32 v[230:231], v[48:49], v[202:203], v[210:211]
	v_pk_fma_f32 v[228:229], v[54:55], v[200:201], v[208:209]
	v_pk_fma_f32 v[232:233], v[50:51], v[204:205], v[212:213]
	v_fmac_f32_dpp v226, v52, v190 row_shr:1 row_mask:0xf bank_mask:0xf
	v_fmac_f32_dpp v230, v48, v194 row_shr:1 row_mask:0xf bank_mask:0xf
	v_fmac_f32_dpp v227, v53, v191 row_shr:1 row_mask:0xf bank_mask:0xf
	v_fmac_f32_dpp v231, v49, v195 row_shr:1 row_mask:0xf bank_mask:0xf
	v_fmac_f32_dpp v228, v54, v192 row_shr:1 row_mask:0xf bank_mask:0xf
	v_fmac_f32_dpp v232, v50, v196 row_shr:1 row_mask:0xf bank_mask:0xf
	v_fmac_f32_dpp v229, v55, v193 row_shr:1 row_mask:0xf bank_mask:0xf
	v_fmac_f32_dpp v233, v51, v197 row_shr:1 row_mask:0xf bank_mask:0xf
	v_fmac_f32_dpp v226, v40, v190 row_shl:15 row_mask:0xf bank_mask:0xf
	v_fmac_f32_dpp v230, v28, v194 row_shl:15 row_mask:0xf bank_mask:0xf
	v_fmac_f32_dpp v227, v41, v191 row_shl:15 row_mask:0xf bank_mask:0xf
	v_fmac_f32_dpp v231, v29, v195 row_shl:15 row_mask:0xf bank_mask:0xf
	v_fmac_f32_dpp v228, v42, v192 row_shl:15 row_mask:0xf bank_mask:0xf
	v_fmac_f32_dpp v232, v30, v196 row_shl:15 row_mask:0xf bank_mask:0xf
	v_fmac_f32_dpp v229, v43, v193 row_shl:15 row_mask:0xf bank_mask:0xf
	v_fmac_f32_dpp v233, v31, v197 row_shl:15 row_mask:0xf bank_mask:0xf
	v_fmac_f32_dpp v226, v52, v182 row_shr:2 row_mask:0xf bank_mask:0xf
	v_fmac_f32_dpp v230, v48, v186 row_shr:2 row_mask:0xf bank_mask:0xf
	v_fmac_f32_dpp v227, v53, v183 row_shr:2 row_mask:0xf bank_mask:0xf
	v_fmac_f32_dpp v231, v49, v187 row_shr:2 row_mask:0xf bank_mask:0xf
	v_fmac_f32_dpp v228, v54, v184 row_shr:2 row_mask:0xf bank_mask:0xf
	v_fmac_f32_dpp v232, v50, v188 row_shr:2 row_mask:0xf bank_mask:0xf
	v_fmac_f32_dpp v229, v55, v185 row_shr:2 row_mask:0xf bank_mask:0xf
	v_fmac_f32_dpp v233, v51, v189 row_shr:2 row_mask:0xf bank_mask:0xf
	v_fmac_f32_dpp v226, v40, v182 row_shl:14 row_mask:0xf bank_mask:0xf
	v_fmac_f32_dpp v230, v28, v186 row_shl:14 row_mask:0xf bank_mask:0xf
	v_fmac_f32_dpp v227, v41, v183 row_shl:14 row_mask:0xf bank_mask:0xf
	v_fmac_f32_dpp v231, v29, v187 row_shl:14 row_mask:0xf bank_mask:0xf
	v_fmac_f32_dpp v228, v42, v184 row_shl:14 row_mask:0xf bank_mask:0xf
	v_fmac_f32_dpp v232, v30, v188 row_shl:14 row_mask:0xf bank_mask:0xf
	v_fmac_f32_dpp v229, v43, v185 row_shl:14 row_mask:0xf bank_mask:0xf
	v_fmac_f32_dpp v233, v31, v189 row_shl:14 row_mask:0xf bank_mask:0xf
	v_pk_mul_f32 v[234:235], v[226:227], v[226:227]
	v_pk_mul_f32 v[238:239], v[230:231], v[230:231]
	v_pk_mul_f32 v[236:237], v[228:229], v[228:229]
	v_pk_mul_f32 v[240:241], v[232:233], v[232:233]
	v_pk_fma_f32 v[234:235], v[234:235], v[144:145], v[142:143]
	v_pk_fma_f32 v[238:239], v[238:239], v[144:145], v[142:143]
	v_pk_fma_f32 v[236:237], v[236:237], v[144:145], v[142:143]
	v_pk_fma_f32 v[240:241], v[240:241], v[144:145], v[142:143]
	v_pk_mul_f32 v[234:235], v[234:235], v[226:227]
	v_pk_mul_f32 v[238:239], v[238:239], v[230:231]
	v_pk_mul_f32 v[236:237], v[236:237], v[228:229]
	v_pk_mul_f32 v[240:241], v[240:241], v[232:233]
	v_exp_f32_e32 v234, v234
	v_exp_f32_e32 v238, v238
	v_exp_f32_e32 v235, v235
	v_exp_f32_e32 v239, v239
	v_exp_f32_e32 v236, v236
	v_exp_f32_e32 v240, v240
	v_exp_f32_e32 v237, v237
	v_exp_f32_e32 v241, v241
	s_nop 0
	s_nop 0
	v_pk_add_f32 v[234:235], v[234:235], v[146:147]
	v_pk_add_f32 v[238:239], v[238:239], v[146:147]
	v_pk_add_f32 v[236:237], v[236:237], v[146:147]
	v_pk_add_f32 v[240:241], v[240:241], v[146:147]
	v_rcp_f32_e32 v234, v234
	v_rcp_f32_e32 v238, v238
	v_rcp_f32_e32 v235, v235
	v_rcp_f32_e32 v239, v239
	v_rcp_f32_e32 v236, v236
	v_rcp_f32_e32 v240, v240
	v_rcp_f32_e32 v237, v237
	v_rcp_f32_e32 v241, v241
	s_nop 0
	s_nop 0
	v_pk_mul_f32 v[234:235], v[234:235], v[226:227]
	v_pk_mul_f32 v[238:239], v[238:239], v[230:231]
	v_pk_mul_f32 v[236:237], v[236:237], v[228:229]
	v_pk_mul_f32 v[240:241], v[240:241], v[232:233]
	v_pk_mul_f32 v[8:9], v[8:9], v[234:235]
	v_pk_mul_f32 v[0:1], v[0:1], v[238:239]
	v_pk_mul_f32 v[10:11], v[10:11], v[236:237]
	v_pk_mul_f32 v[2:3], v[2:3], v[240:241]
	v_cvt_pk_bf16_f32 v8, v8, v9
	v_cvt_pk_bf16_f32 v9, v10, v11
	v_cvt_pk_bf16_f32 v10, v0, v1
	v_cvt_pk_bf16_f32 v11, v2, v3
	v_add_u32_e32 v245, 0xf2000, v225
	global_store_dwordx4 v245, v[8:11], s[46:47]
	v_pk_fma_f32 v[226:227], v[40:41], v[198:199], v[206:207]
	v_pk_fma_f32 v[230:231], v[28:29], v[202:203], v[210:211]
	v_pk_fma_f32 v[228:229], v[42:43], v[200:201], v[208:209]
	v_pk_fma_f32 v[232:233], v[30:31], v[204:205], v[212:213]
	v_fmac_f32_dpp v226, v40, v190 row_shr:1 row_mask:0xf bank_mask:0xf
	v_fmac_f32_dpp v230, v28, v194 row_shr:1 row_mask:0xf bank_mask:0xf
	v_fmac_f32_dpp v227, v41, v191 row_shr:1 row_mask:0xf bank_mask:0xf
	v_fmac_f32_dpp v231, v29, v195 row_shr:1 row_mask:0xf bank_mask:0xf
	v_fmac_f32_dpp v228, v42, v192 row_shr:1 row_mask:0xf bank_mask:0xf
	v_fmac_f32_dpp v232, v30, v196 row_shr:1 row_mask:0xf bank_mask:0xf
	v_fmac_f32_dpp v229, v43, v193 row_shr:1 row_mask:0xf bank_mask:0xf
	v_fmac_f32_dpp v233, v31, v197 row_shr:1 row_mask:0xf bank_mask:0xf
	v_fmac_f32_dpp v226, v44, v190 row_shl:15 row_mask:0xf bank_mask:0xf
	v_fmac_f32_dpp v230, v32, v194 row_shl:15 row_mask:0xf bank_mask:0xf
	v_fmac_f32_dpp v227, v45, v191 row_shl:15 row_mask:0xf bank_mask:0xf
	v_fmac_f32_dpp v231, v33, v195 row_shl:15 row_mask:0xf bank_mask:0xf
	v_fmac_f32_dpp v228, v46, v192 row_shl:15 row_mask:0xf bank_mask:0xf
	v_fmac_f32_dpp v232, v34, v196 row_shl:15 row_mask:0xf bank_mask:0xf
	v_fmac_f32_dpp v229, v47, v193 row_shl:15 row_mask:0xf bank_mask:0xf
	v_fmac_f32_dpp v233, v35, v197 row_shl:15 row_mask:0xf bank_mask:0xf
	v_fmac_f32_dpp v226, v40, v182 row_shr:2 row_mask:0xf bank_mask:0xf
	v_fmac_f32_dpp v230, v28, v186 row_shr:2 row_mask:0xf bank_mask:0xf
	v_fmac_f32_dpp v227, v41, v183 row_shr:2 row_mask:0xf bank_mask:0xf
	v_fmac_f32_dpp v231, v29, v187 row_shr:2 row_mask:0xf bank_mask:0xf
	v_fmac_f32_dpp v228, v42, v184 row_shr:2 row_mask:0xf bank_mask:0xf
	v_fmac_f32_dpp v232, v30, v188 row_shr:2 row_mask:0xf bank_mask:0xf
	v_fmac_f32_dpp v229, v43, v185 row_shr:2 row_mask:0xf bank_mask:0xf
	v_fmac_f32_dpp v233, v31, v189 row_shr:2 row_mask:0xf bank_mask:0xf
	v_fmac_f32_dpp v226, v44, v182 row_shl:14 row_mask:0xf bank_mask:0xf
	v_fmac_f32_dpp v230, v32, v186 row_shl:14 row_mask:0xf bank_mask:0xf
	v_fmac_f32_dpp v227, v45, v183 row_shl:14 row_mask:0xf bank_mask:0xf
	v_fmac_f32_dpp v231, v33, v187 row_shl:14 row_mask:0xf bank_mask:0xf
	v_fmac_f32_dpp v228, v46, v184 row_shl:14 row_mask:0xf bank_mask:0xf
	v_fmac_f32_dpp v232, v34, v188 row_shl:14 row_mask:0xf bank_mask:0xf
	v_fmac_f32_dpp v229, v47, v185 row_shl:14 row_mask:0xf bank_mask:0xf
	v_fmac_f32_dpp v233, v35, v189 row_shl:14 row_mask:0xf bank_mask:0xf
	v_pk_mul_f32 v[234:235], v[226:227], v[226:227]
	v_pk_mul_f32 v[238:239], v[230:231], v[230:231]
	v_pk_mul_f32 v[236:237], v[228:229], v[228:229]
	v_pk_mul_f32 v[240:241], v[232:233], v[232:233]
	v_pk_fma_f32 v[234:235], v[234:235], v[144:145], v[142:143]
	v_pk_fma_f32 v[238:239], v[238:239], v[144:145], v[142:143]
	v_pk_fma_f32 v[236:237], v[236:237], v[144:145], v[142:143]
	v_pk_fma_f32 v[240:241], v[240:241], v[144:145], v[142:143]
	v_pk_mul_f32 v[234:235], v[234:235], v[226:227]
	v_pk_mul_f32 v[238:239], v[238:239], v[230:231]
	v_pk_mul_f32 v[236:237], v[236:237], v[228:229]
	v_pk_mul_f32 v[240:241], v[240:241], v[232:233]
	v_exp_f32_e32 v234, v234
	v_exp_f32_e32 v238, v238
	v_exp_f32_e32 v235, v235
	v_exp_f32_e32 v239, v239
	v_exp_f32_e32 v236, v236
	v_exp_f32_e32 v240, v240
	v_exp_f32_e32 v237, v237
	v_exp_f32_e32 v241, v241
	s_nop 0
	s_nop 0
	v_pk_add_f32 v[234:235], v[234:235], v[146:147]
	v_pk_add_f32 v[238:239], v[238:239], v[146:147]
	v_pk_add_f32 v[236:237], v[236:237], v[146:147]
	v_pk_add_f32 v[240:241], v[240:241], v[146:147]
	v_rcp_f32_e32 v234, v234
	v_rcp_f32_e32 v238, v238
	v_rcp_f32_e32 v235, v235
	v_rcp_f32_e32 v239, v239
	v_rcp_f32_e32 v236, v236
	v_rcp_f32_e32 v240, v240
	v_rcp_f32_e32 v237, v237
	v_rcp_f32_e32 v241, v241
	s_nop 0
	s_nop 0
	v_pk_mul_f32 v[234:235], v[234:235], v[226:227]
	v_pk_mul_f32 v[238:239], v[238:239], v[230:231]
	v_pk_mul_f32 v[236:237], v[236:237], v[228:229]
	v_pk_mul_f32 v[240:241], v[240:241], v[232:233]
	v_pk_mul_f32 v[16:17], v[16:17], v[234:235]
	v_pk_mul_f32 v[4:5], v[4:5], v[238:239]
	v_pk_mul_f32 v[18:19], v[18:19], v[236:237]
	v_pk_mul_f32 v[6:7], v[6:7], v[240:241]
	v_cvt_pk_bf16_f32 v16, v16, v17
	v_cvt_pk_bf16_f32 v17, v18, v19
	v_cvt_pk_bf16_f32 v18, v4, v5
	v_cvt_pk_bf16_f32 v19, v6, v7
	v_add_u32_e32 v244, 0xdc000, v225
	global_store_dwordx4 v244, v[16:19], s[46:47]
	v_pk_fma_f32 v[226:227], v[44:45], v[198:199], v[206:207]
	v_pk_fma_f32 v[230:231], v[32:33], v[202:203], v[210:211]
	v_pk_fma_f32 v[228:229], v[46:47], v[200:201], v[208:209]
	v_pk_fma_f32 v[232:233], v[34:35], v[204:205], v[212:213]
	v_fmac_f32_dpp v226, v44, v190 row_shr:1 row_mask:0xf bank_mask:0xf
	v_fmac_f32_dpp v230, v32, v194 row_shr:1 row_mask:0xf bank_mask:0xf
	v_fmac_f32_dpp v227, v45, v191 row_shr:1 row_mask:0xf bank_mask:0xf
	v_fmac_f32_dpp v231, v33, v195 row_shr:1 row_mask:0xf bank_mask:0xf
	v_fmac_f32_dpp v228, v46, v192 row_shr:1 row_mask:0xf bank_mask:0xf
	v_fmac_f32_dpp v232, v34, v196 row_shr:1 row_mask:0xf bank_mask:0xf
	v_fmac_f32_dpp v229, v47, v193 row_shr:1 row_mask:0xf bank_mask:0xf
	v_fmac_f32_dpp v233, v35, v197 row_shr:1 row_mask:0xf bank_mask:0xf
	v_fmac_f32_dpp v226, v60, v190 row_shl:15 row_mask:0xf bank_mask:0xf
	v_fmac_f32_dpp v230, v56, v194 row_shl:15 row_mask:0xf bank_mask:0xf
	v_fmac_f32_dpp v227, v61, v191 row_shl:15 row_mask:0xf bank_mask:0xf
	v_fmac_f32_dpp v231, v57, v195 row_shl:15 row_mask:0xf bank_mask:0xf
	v_fmac_f32_dpp v228, v62, v192 row_shl:15 row_mask:0xf bank_mask:0xf
	v_fmac_f32_dpp v232, v58, v196 row_shl:15 row_mask:0xf bank_mask:0xf
	v_fmac_f32_dpp v229, v63, v193 row_shl:15 row_mask:0xf bank_mask:0xf
	v_fmac_f32_dpp v233, v59, v197 row_shl:15 row_mask:0xf bank_mask:0xf
	v_fmac_f32_dpp v226, v44, v182 row_shr:2 row_mask:0xf bank_mask:0xf
	v_fmac_f32_dpp v230, v32, v186 row_shr:2 row_mask:0xf bank_mask:0xf
	v_fmac_f32_dpp v227, v45, v183 row_shr:2 row_mask:0xf bank_mask:0xf
	v_fmac_f32_dpp v231, v33, v187 row_shr:2 row_mask:0xf bank_mask:0xf
	v_fmac_f32_dpp v228, v46, v184 row_shr:2 row_mask:0xf bank_mask:0xf
	v_fmac_f32_dpp v232, v34, v188 row_shr:2 row_mask:0xf bank_mask:0xf
	v_fmac_f32_dpp v229, v47, v185 row_shr:2 row_mask:0xf bank_mask:0xf
	v_fmac_f32_dpp v233, v35, v189 row_shr:2 row_mask:0xf bank_mask:0xf
	v_fmac_f32_dpp v226, v60, v182 row_shl:14 row_mask:0xf bank_mask:0xf
	v_fmac_f32_dpp v230, v56, v186 row_shl:14 row_mask:0xf bank_mask:0xf
	v_fmac_f32_dpp v227, v61, v183 row_shl:14 row_mask:0xf bank_mask:0xf
	v_fmac_f32_dpp v231, v57, v187 row_shl:14 row_mask:0xf bank_mask:0xf
	v_fmac_f32_dpp v228, v62, v184 row_shl:14 row_mask:0xf bank_mask:0xf
	v_fmac_f32_dpp v232, v58, v188 row_shl:14 row_mask:0xf bank_mask:0xf
	v_fmac_f32_dpp v229, v63, v185 row_shl:14 row_mask:0xf bank_mask:0xf
	v_fmac_f32_dpp v233, v59, v189 row_shl:14 row_mask:0xf bank_mask:0xf
	v_pk_mul_f32 v[234:235], v[226:227], v[226:227]
	v_pk_mul_f32 v[238:239], v[230:231], v[230:231]
	v_pk_mul_f32 v[236:237], v[228:229], v[228:229]
	v_pk_mul_f32 v[240:241], v[232:233], v[232:233]
	v_pk_fma_f32 v[234:235], v[234:235], v[144:145], v[142:143]
	v_pk_fma_f32 v[238:239], v[238:239], v[144:145], v[142:143]
	v_pk_fma_f32 v[236:237], v[236:237], v[144:145], v[142:143]
	v_pk_fma_f32 v[240:241], v[240:241], v[144:145], v[142:143]
	v_pk_mul_f32 v[234:235], v[234:235], v[226:227]
	v_pk_mul_f32 v[238:239], v[238:239], v[230:231]
	v_pk_mul_f32 v[236:237], v[236:237], v[228:229]
	v_pk_mul_f32 v[240:241], v[240:241], v[232:233]
	v_exp_f32_e32 v234, v234
	v_exp_f32_e32 v238, v238
	v_exp_f32_e32 v235, v235
	v_exp_f32_e32 v239, v239
	v_exp_f32_e32 v236, v236
	v_exp_f32_e32 v240, v240
	v_exp_f32_e32 v237, v237
	v_exp_f32_e32 v241, v241
	s_nop 0
	s_nop 0
	v_pk_add_f32 v[234:235], v[234:235], v[146:147]
	v_pk_add_f32 v[238:239], v[238:239], v[146:147]
	v_pk_add_f32 v[236:237], v[236:237], v[146:147]
	v_pk_add_f32 v[240:241], v[240:241], v[146:147]
	v_rcp_f32_e32 v234, v234
	v_rcp_f32_e32 v238, v238
	v_rcp_f32_e32 v235, v235
	v_rcp_f32_e32 v239, v239
	v_rcp_f32_e32 v236, v236
	v_rcp_f32_e32 v240, v240
	v_rcp_f32_e32 v237, v237
	v_rcp_f32_e32 v241, v241
	s_nop 0
	s_nop 0
	v_pk_mul_f32 v[234:235], v[234:235], v[226:227]
	v_pk_mul_f32 v[238:239], v[238:239], v[230:231]
	v_pk_mul_f32 v[236:237], v[236:237], v[228:229]
	v_pk_mul_f32 v[240:241], v[240:241], v[232:233]
	v_pk_mul_f32 v[20:21], v[20:21], v[234:235]
	v_pk_mul_f32 v[12:13], v[12:13], v[238:239]
	v_pk_mul_f32 v[22:23], v[22:23], v[236:237]
	v_pk_mul_f32 v[14:15], v[14:15], v[240:241]
	v_cvt_pk_bf16_f32 v20, v20, v21
	v_cvt_pk_bf16_f32 v21, v22, v23
	v_cvt_pk_bf16_f32 v22, v12, v13
	v_cvt_pk_bf16_f32 v23, v14, v15
	v_add_u32_e32 v243, 0xc6000, v225
	global_store_dwordx4 v243, v[20:23], s[46:47]
	v_pk_fma_f32 v[226:227], v[60:61], v[198:199], v[206:207]
	v_pk_fma_f32 v[230:231], v[56:57], v[202:203], v[210:211]
	v_pk_fma_f32 v[228:229], v[62:63], v[200:201], v[208:209]
	v_pk_fma_f32 v[232:233], v[58:59], v[204:205], v[212:213]
	v_fmac_f32_dpp v226, v60, v190 row_shr:1 row_mask:0xf bank_mask:0xf
	v_fmac_f32_dpp v230, v56, v194 row_shr:1 row_mask:0xf bank_mask:0xf
	v_fmac_f32_dpp v227, v61, v191 row_shr:1 row_mask:0xf bank_mask:0xf
	v_fmac_f32_dpp v231, v57, v195 row_shr:1 row_mask:0xf bank_mask:0xf
	v_fmac_f32_dpp v228, v62, v192 row_shr:1 row_mask:0xf bank_mask:0xf
	v_fmac_f32_dpp v232, v58, v196 row_shr:1 row_mask:0xf bank_mask:0xf
	v_fmac_f32_dpp v229, v63, v193 row_shr:1 row_mask:0xf bank_mask:0xf
	v_fmac_f32_dpp v233, v59, v197 row_shr:1 row_mask:0xf bank_mask:0xf
	v_fmac_f32_dpp v226, v60, v182 row_shr:2 row_mask:0xf bank_mask:0xf
	v_fmac_f32_dpp v230, v56, v186 row_shr:2 row_mask:0xf bank_mask:0xf
	v_fmac_f32_dpp v227, v61, v183 row_shr:2 row_mask:0xf bank_mask:0xf
	v_fmac_f32_dpp v231, v57, v187 row_shr:2 row_mask:0xf bank_mask:0xf
	v_fmac_f32_dpp v228, v62, v184 row_shr:2 row_mask:0xf bank_mask:0xf
	v_fmac_f32_dpp v232, v58, v188 row_shr:2 row_mask:0xf bank_mask:0xf
	v_fmac_f32_dpp v229, v63, v185 row_shr:2 row_mask:0xf bank_mask:0xf
	v_fmac_f32_dpp v233, v59, v189 row_shr:2 row_mask:0xf bank_mask:0xf
	v_pk_mul_f32 v[234:235], v[226:227], v[226:227]
	v_pk_mul_f32 v[238:239], v[230:231], v[230:231]
	v_pk_mul_f32 v[236:237], v[228:229], v[228:229]
	v_pk_mul_f32 v[240:241], v[232:233], v[232:233]
	v_pk_fma_f32 v[234:235], v[234:235], v[144:145], v[142:143]
	v_pk_fma_f32 v[238:239], v[238:239], v[144:145], v[142:143]
	v_pk_fma_f32 v[236:237], v[236:237], v[144:145], v[142:143]
	v_pk_fma_f32 v[240:241], v[240:241], v[144:145], v[142:143]
	v_pk_mul_f32 v[234:235], v[234:235], v[226:227]
	v_pk_mul_f32 v[238:239], v[238:239], v[230:231]
	v_pk_mul_f32 v[236:237], v[236:237], v[228:229]
	v_pk_mul_f32 v[240:241], v[240:241], v[232:233]
	v_exp_f32_e32 v234, v234
	v_exp_f32_e32 v238, v238
	v_exp_f32_e32 v235, v235
	v_exp_f32_e32 v239, v239
	v_exp_f32_e32 v236, v236
	v_exp_f32_e32 v240, v240
	v_exp_f32_e32 v237, v237
	v_exp_f32_e32 v241, v241
	s_nop 0
	s_nop 0
	v_pk_add_f32 v[234:235], v[234:235], v[146:147]
	v_pk_add_f32 v[238:239], v[238:239], v[146:147]
	v_pk_add_f32 v[236:237], v[236:237], v[146:147]
	v_pk_add_f32 v[240:241], v[240:241], v[146:147]
	v_rcp_f32_e32 v234, v234
	v_rcp_f32_e32 v238, v238
	v_rcp_f32_e32 v235, v235
	v_rcp_f32_e32 v239, v239
	v_rcp_f32_e32 v236, v236
	v_rcp_f32_e32 v240, v240
	v_rcp_f32_e32 v237, v237
	v_rcp_f32_e32 v241, v241
	s_nop 0
	s_nop 0
	v_pk_mul_f32 v[234:235], v[234:235], v[226:227]
	v_pk_mul_f32 v[238:239], v[238:239], v[230:231]
	v_pk_mul_f32 v[236:237], v[236:237], v[228:229]
	v_pk_mul_f32 v[240:241], v[240:241], v[232:233]
	v_pk_mul_f32 v[234:235], v[36:37], v[234:235]
	v_pk_mul_f32 v[238:239], v[24:25], v[238:239]
	v_pk_mul_f32 v[236:237], v[38:39], v[236:237]
	v_pk_mul_f32 v[240:241], v[26:27], v[240:241]
	v_cndmask_b32_e32 v36, v234, v36, vcc
	v_cndmask_b32_e32 v24, v238, v24, vcc
	v_cndmask_b32_e32 v37, v235, v37, vcc
	v_cndmask_b32_e32 v25, v239, v25, vcc
	v_cndmask_b32_e32 v38, v236, v38, vcc
	v_cndmask_b32_e32 v26, v240, v26, vcc
	v_cndmask_b32_e32 v39, v237, v39, vcc
	v_cndmask_b32_e32 v27, v241, v27, vcc
	v_cvt_pk_bf16_f32 v36, v36, v37
	v_cvt_pk_bf16_f32 v37, v38, v39
	v_cvt_pk_bf16_f32 v38, v24, v25
	v_cvt_pk_bf16_f32 v39, v26, v27
	v_add_u32_e32 v242, 0xb0000, v225
	global_store_dwordx4 v242, v[36:39], s[46:47]
	s_andn2_b64 vcc, exec, s[0:1]
	s_mov_b64 s[0:1], -1
	s_cbranch_vccnz .LBB0_1511
	s_andn2_b64 vcc, exec, s[42:43]
	s_cbranch_vccnz .LBB0_1510
	s_barrier
	s_branch .LBB0_1510
